# GDN step: beta folded into the V image and the per-token scalar pair (alpha, beta*alpha) at pre-processing time; u = fma only, one VALU op fewer on the per-token chain
# speedup vs baseline: 1.0079x; 1.0079x over previous
; #define LAS __attribute__((address_space(3)))
; __device__ __forceinline__ float hload(const f16_t* p) { return (float)(*p); }
; __device__ __forceinline__ float sigmoidf_(float x) { return 1.0f / (1.0f + __expf(-x)); }
; __device__ __forceinline__ float softplusf_(float x) { return x > 20.f ? x : log1pf(expf(x)); }
; __device__ __forceinline__ float red8(float x) { x = red4(x); x += dppf<0x141>(x); return x; }
; __device__ __forceinline__ void u4f(const u32x4& u, float (&f)[8]) { h2f(u.x, f[0], f[1]); h2f(u.y, f[2], f[3]); h2f(u.z, f[4], f[5]); h2f(u.w, f[6], f[7]); }
; template <int MIX, bool SAMPLE>
; __device__ __forceinline__ void rec_load(Raw<MIX>& R, const f16_t* proj, int chunk, int sg, int head, int vcol0) {
;     ...
;     } else if constexpr (MIX == 1) {
;         R.q = *(const u32x4*)(rowp + C_GQKV + head * 64 + cgi * 8);
;         R.k = *(const u32x4*)(rowp + C_GQKV + 256 + head * 64 + cgi * 8);
;         R.v = *(const u32x2*)(rowp + C_GQKV + 512 + head * 64 + vcol0 + cgi * 4);
;         R.ga = hload(rowp + C_GA + head); R.gb = hload(rowp + C_GB + head);
; template <int MIX, bool SAMPLE>
; __device__ __forceinline__ void rec_process(const Raw<MIX>& R, const MixPar& par, int l, LAS float* L, int chunk, int sg, int head) {
;     ...
;     } else if constexpr (MIX == 1) {
;         float q[8], k[8], v[4]; u4f(R.q, q); u4f(R.k, k); u2f(R.v, v);
;         float sq = 0.f, sk = 0.f;
; #pragma unroll
;         for (int i = 0; i < 8; ++i) { sq += q[i] * q[i]; sk += k[i] * k[i]; }
;         sq = red8(sq); sk = red8(sk);
;         const float rq = rsqrtf(sq + EPS) * 0.125f, rk = rsqrtf(sk + EPS);
;         float kq = 0.f;
; #pragma unroll
;         for (int i = 0; i < 8; ++i) { q[i] *= rq; k[i] *= rk; kq += q[i] * k[i]; }
;         kq = red8(kq);
;         *(LAS f32x4*)(L + C::OFF_Q + s * 64 + cgi * 8) = (f32x4){q[0], q[1], q[2], q[3]}; *(LAS f32x4*)(L + C::OFF_Q + s * 64 + cgi * 8 + 4) = (f32x4){q[4], q[5], q[6], q[7]};
;         *(LAS f32x4*)(L + C::OFF_K + s * 64 + cgi * 8) = (f32x4){k[0], k[1], k[2], k[3]}; *(LAS f32x4*)(L + C::OFF_K + s * 64 + cgi * 8 + 4) = (f32x4){k[4], k[5], k[6], k[7]};
;         *(LAS f32x4*)(L + C::OFF_V + s * 32 + cgi * 4) = (f32x4){v[0], v[1], v[2], v[3]};
;         if (cgi == 0) { const float a = expf(-par.f[0] * softplusf_(R.ga + par.f[1]));
;             *(LAS f32x4*)(L + C::OFF_SC + s * 4) = (f32x4){a, sigmoidf_(R.gb), kq, 0.f}; }
.LBB0_403:
	s_and_b64 vcc, exec, s[4:5]
	s_cbranch_vccz .LBB0_174
	s_mov_b64 s[2:3], s[0:1]
	s_mov_b64 s[4:5], s[0:1]
	s_load_dwordx2 s[2:3], s[2:3], 0xe0
	s_load_dwordx2 s[52:53], s[4:5], 0xe0
	s_waitcnt vmcnt(6)
	v_mov_b32_e32 v10, v202
	s_waitcnt vmcnt(2)
	v_mov_b32_e32 v0, v202
	s_mov_b64 s[4:5], s[0:1]
	s_load_dwordx2 s[4:5], s[4:5], 0x68
	v_readlane_b32 s6, v252, 59
	s_or_b32 s6, s30, s6
	s_lshl_b32 s6, s6, 2
	v_mov_b32_e32 v0, s6
	s_waitcnt lgkmcnt(0)
	global_load_dword v1, v0, s[4:5]
	s_mov_b64 s[4:5], s[0:1]
	s_load_dwordx2 s[4:5], s[4:5], 0x70
	s_add_u32 s54, s2, 0x5600000
	s_addc_u32 s55, s3, 0
	s_lshl_b32 s10, s31, 11
	s_lshl_b32 s78, s30, 7
	s_waitcnt lgkmcnt(0)
	global_load_dword v18, v0, s[4:5]
	s_waitcnt vmcnt(3)
	v_mov_b32_e32 v7, v17
	s_lshl_b32 s56, s30, 1
	s_mov_b32 s57, s79
	v_mov_b32_e32 v11, v202
	s_waitcnt vmcnt(1)
	v_mul_f32_e32 v0, 0x3fb8aa3b, v1
	v_fma_f32 v2, v1, s19, -v0
	v_rndne_f32_e32 v3, v0
	v_fmac_f32_e32 v2, 0x32a5705f, v1
	v_sub_f32_e32 v0, v0, v3
	v_add_f32_e32 v0, v0, v2
	v_exp_f32_e32 v0, v0
	v_cvt_i32_f32_e32 v2, v3
	v_cmp_ngt_f32_e32 vcc, s96, v1
	v_ldexp_f32 v0, v0, v2
	s_nop 0
	v_cndmask_b32_e32 v0, 0, v0, vcc
	v_cmp_nlt_f32_e32 vcc, s97, v1
	s_nop 1
	v_cndmask_b32_e32 v4, v216, v0, vcc
	v_mov_b32_e32 v0, v202
	v_xor_b32_e32 v19, 0x80000000, v4
	v_ashrrev_i32_e32 v1, 3, v0
	v_and_b32_e32 v5, 7, v0
	v_add_u32_e32 v2, s10, v1
	v_mov_b64_e32 v[0:1], s[54:55]
	v_mad_i64_i32 v[2:3], s[2:3], v2, s18, v[0:1]
	v_lshl_add_u64 v[0:1], v[2:3], 0, s[78:79]
	v_lshlrev_b32_e32 v6, 4, v5
	v_lshl_add_u64 v[6:7], v[0:1], 0, v[6:7]
	global_load_dwordx4 v[12:15], v[6:7], off offset:2048
	global_load_dwordx4 v[20:23], v[6:7], off offset:2560
	s_lshl_b32 s78, s34, 6
	v_lshlrev_b32_e32 v16, 3, v5
	v_lshl_add_u64 v[0:1], v[0:1], 0, s[78:79]
	v_lshl_add_u64 v[0:1], v[0:1], 0, v[16:17]
	global_load_dwordx2 v[0:1], v[0:1], off offset:3072
	v_lshl_add_u64 v[2:3], v[2:3], 0, s[56:57]
	v_add_co_u32_e32 v2, vcc, s20, v2
	s_waitcnt vmcnt(2)
	v_cvt_f32_f16_e32 v30, v12
	v_addc_co_u32_e32 v3, vcc, 0, v3, vcc
	global_load_ushort v7, v[2:3], off
	global_load_ushort v5, v[2:3], off offset:8
	v_cvt_f32_f16_sdwa v31, v12 dst_sel:DWORD dst_unused:UNUSED_PAD src0_sel:WORD_1
	s_waitcnt vmcnt(3)
	v_cvt_f32_f16_e32 v38, v20
	v_cvt_f32_f16_sdwa v39, v20 dst_sel:DWORD dst_unused:UNUSED_PAD src0_sel:WORD_1
	v_cvt_f32_f16_e32 v34, v13
	v_cvt_f32_f16_sdwa v35, v13 dst_sel:DWORD dst_unused:UNUSED_PAD src0_sel:WORD_1
	v_cvt_f32_f16_e32 v42, v21
	v_cvt_f32_f16_sdwa v43, v21 dst_sel:DWORD dst_unused:UNUSED_PAD src0_sel:WORD_1
	v_cvt_f32_f16_e32 v8, v14
	v_cvt_f32_f16_sdwa v9, v14 dst_sel:DWORD dst_unused:UNUSED_PAD src0_sel:WORD_1
	v_cvt_f32_f16_e32 v2, v22
	v_cvt_f32_f16_sdwa v3, v22 dst_sel:DWORD dst_unused:UNUSED_PAD src0_sel:WORD_1
	v_pk_mul_f32 v[32:33], v[30:31], v[30:31]
	v_pk_mul_f32 v[40:41], v[38:39], v[38:39]
	v_cvt_f32_f16_e32 v28, v15
	v_cvt_f32_f16_sdwa v29, v15 dst_sel:DWORD dst_unused:UNUSED_PAD src0_sel:WORD_1
	v_pk_mul_f32 v[12:13], v[34:35], v[34:35]
	v_cvt_f32_f16_e32 v36, v23
	v_cvt_f32_f16_sdwa v37, v23 dst_sel:DWORD dst_unused:UNUSED_PAD src0_sel:WORD_1
	v_pk_mul_f32 v[20:21], v[42:43], v[42:43]
	v_mov_b32_e32 v44, v40
	v_mov_b32_e32 v45, v32
	v_mov_b32_e32 v32, v41
	v_pk_add_f32 v[32:33], v[44:45], v[32:33]
	v_mov_b32_e32 v40, v20
	v_mov_b32_e32 v41, v12
	v_pk_mul_f32 v[24:25], v[8:9], v[8:9]
	v_pk_mul_f32 v[26:27], v[2:3], v[2:3]
	v_pk_add_f32 v[32:33], v[40:41], v[32:33]
	v_mov_b32_e32 v12, v21
	v_pk_add_f32 v[12:13], v[12:13], v[32:33]
	v_mov_b32_e32 v20, v26
	v_mov_b32_e32 v21, v24
	v_pk_mul_f32 v[14:15], v[28:29], v[28:29]
	v_pk_mul_f32 v[22:23], v[36:37], v[36:37]
	v_pk_add_f32 v[12:13], v[20:21], v[12:13]
	v_mov_b32_e32 v24, v27
	v_pk_add_f32 v[12:13], v[24:25], v[12:13]
	v_mov_b32_e32 v20, v22
	v_mov_b32_e32 v21, v14
	v_pk_add_f32 v[12:13], v[20:21], v[12:13]
	v_mov_b32_e32 v14, v23
	v_pk_add_f32 v[12:13], v[14:15], v[12:13]
	s_waitcnt vmcnt(2)
	v_cvt_f32_f16_e32 v32, v0
	v_ashrrev_i32_e32 v6, 3, v11
	v_mov_b32_dpp v15, v13 quad_perm:[1,0,3,2] row_mask:0xf bank_mask:0xf bound_ctrl:1
	v_mov_b32_dpp v14, v12 quad_perm:[1,0,3,2] row_mask:0xf bank_mask:0xf bound_ctrl:1
	v_pk_add_f32 v[12:13], v[12:13], v[14:15]
	v_cvt_f32_f16_sdwa v33, v0 dst_sel:DWORD dst_unused:UNUSED_PAD src0_sel:WORD_1
	s_nop 0
	v_mov_b32_dpp v15, v13 quad_perm:[2,3,0,1] row_mask:0xf bank_mask:0xf bound_ctrl:1
	v_mov_b32_dpp v14, v12 quad_perm:[2,3,0,1] row_mask:0xf bank_mask:0xf bound_ctrl:1
	v_pk_add_f32 v[12:13], v[12:13], v[14:15]
	s_nop 1
	v_mov_b32_dpp v15, v13 row_half_mirror row_mask:0xf bank_mask:0xf bound_ctrl:1
	v_mov_b32_dpp v14, v12 row_half_mirror row_mask:0xf bank_mask:0xf bound_ctrl:1
	v_pk_add_f32 v[12:13], v[12:13], v[14:15]
	s_nop 0
	v_pk_add_f32 v[24:25], v[12:13], s[66:67] op_sel_hi:[1,0]
	s_nop 0
	v_mul_f32_e32 v12, 0x4b800000, v25
	v_cmp_gt_f32_e64 s[42:43], s16, v25
	v_cmp_gt_f32_e32 vcc, s16, v24
	s_nop 0
	v_cndmask_b32_e64 v12, v25, v12, s[42:43]
	v_rsq_f32_e32 v12, v12
	s_nop 0
	v_mul_f32_e32 v13, 0x45800000, v12
	v_cndmask_b32_e64 v12, v12, v13, s[42:43]
	v_mul_f32_e32 v16, 0x3e000000, v12
	v_pk_mul_f32 v[20:21], v[16:17], v[8:9] op_sel_hi:[0,1]
	v_mul_f32_e32 v8, 0x4b800000, v24
	v_cndmask_b32_e32 v8, v24, v8, vcc
	v_rsq_f32_e32 v8, v8
	v_pk_mul_f32 v[12:13], v[16:17], v[30:31] op_sel_hi:[0,1]
	v_pk_mul_f32 v[14:15], v[16:17], v[34:35] op_sel_hi:[0,1]
	v_pk_mul_f32 v[22:23], v[16:17], v[28:29] op_sel_hi:[0,1]
	v_mul_f32_e32 v9, 0x45800000, v8
	v_cndmask_b32_e32 v8, v8, v9, vcc
	v_pk_mul_f32 v[24:25], v[8:9], v[38:39] op_sel_hi:[0,1]
	v_pk_mul_f32 v[26:27], v[12:13], v[24:25]
	v_cvt_f32_f16_e32 v34, v1
	v_add_f32_e32 v9, 0, v26
	v_add_f32_e32 v9, v27, v9
	v_pk_mul_f32 v[26:27], v[8:9], v[42:43] op_sel_hi:[0,1]
	v_pk_mul_f32 v[28:29], v[14:15], v[26:27]
	v_cvt_f32_f16_sdwa v35, v1 dst_sel:DWORD dst_unused:UNUSED_PAD src0_sel:WORD_1
	v_add_f32_e32 v9, v28, v9
	v_add_f32_e32 v9, v29, v9
	v_pk_mul_f32 v[28:29], v[8:9], v[2:3] op_sel_hi:[0,1]
	v_pk_mul_f32 v[2:3], v[20:21], v[28:29]
	s_nop 0
	v_add_f32_e32 v2, v2, v9
	v_add_f32_e32 v9, v3, v2
	v_pk_mul_f32 v[30:31], v[8:9], v[36:37] op_sel_hi:[0,1]
	v_pk_mul_f32 v[2:3], v[22:23], v[30:31]
	s_nop 0
	v_add_f32_e32 v2, v2, v9
	v_add_f32_e32 v2, v3, v2
	v_and_b32_e32 v3, 7, v11
	v_cmp_ne_u32_e32 vcc, 0, v3
	v_add_f32_dpp v0, v2, v2 quad_perm:[1,0,3,2] row_mask:0xf bank_mask:0xf bound_ctrl:1
	s_nop 1
	v_add_f32_dpp v1, v0, v0 quad_perm:[2,3,0,1] row_mask:0xf bank_mask:0xf bound_ctrl:1
	v_lshl_add_u32 v0, v6, 8, 0
	v_lshl_add_u32 v8, v3, 5, v0
	ds_write_b128 v8, v[12:15]
	ds_write_b128 v8, v[20:23] offset:16
	ds_write_b128 v8, v[24:27] offset:16384
	ds_write_b128 v8, v[28:31] offset:16400
	v_lshlrev_b32_e32 v8, 7, v6
	v_sub_u32_e32 v0, v0, v8
	v_mov_b32_dpp v2, v1 row_half_mirror row_mask:0xf bank_mask:0xf bound_ctrl:1
	v_lshl_add_u32 v8, v3, 4, v0
	s_waitcnt vmcnt(0)
; #define LAS __attribute__((address_space(3)))
; __device__ __forceinline__ float sigmoidf_(float x) { return 1.0f / (1.0f + __expf(-x)); }
; __device__ __forceinline__ float softplusf_(float x) { return x > 20.f ? x : log1pf(expf(x)); }
; template <int MIX, bool SAMPLE>
; __device__ __forceinline__ void rec_process(const Raw<MIX>& R, const MixPar& par, int l, LAS float* L, int chunk, int sg, int head) {
;     ...
;         *(LAS f32x4*)(L + C::OFF_V + s * 32 + cgi * 4) = (f32x4){v[0], v[1], v[2], v[3]};
;         if (cgi == 0) { const float a = expf(-par.f[0] * softplusf_(R.ga + par.f[1]));
;             *(LAS f32x4*)(L + C::OFF_SC + s * 4) = (f32x4){a, sigmoidf_(R.gb), kq, 0.f}; }
; template <int MIX, bool REDUCE = true>
; __device__ __forceinline__ float rec_step(float (&S)[RecCfg<MIX>::KPL], const LAS float* L, int s, int kg, int vl) {
;     ...
;         const float u = sc[1] * (v - sc[0] * r);
	v_cvt_f32_f16_e32 v60, v5
	v_mul_f32_e32 v60, 0xbfb8aa3b, v60
	v_exp_f32_e32 v60, v60
	s_nop 0
	v_add_f32_e32 v60, 1.0, v60
	v_rcp_f32_e32 v60, v60
	s_nop 0
	v_pk_mul_f32 v[32:33], v[32:33], v[60:61] op_sel_hi:[1,0]
	v_pk_mul_f32 v[34:35], v[34:35], v[60:61] op_sel_hi:[1,0]
	ds_write_b128 v8, v[32:35] offset:32768
	s_and_saveexec_b64 s[2:3], vcc
	s_xor_b64 s[4:5], exec, s[2:3]
	v_xor_b32_e32 v19, 0x80000000, v4
	s_or_saveexec_b64 s[4:5], s[4:5]
	v_readlane_b32 s17, v252, 3
	s_xor_b64 exec, exec, s[4:5]
	s_cbranch_execz .LBB0_410
	s_waitcnt vmcnt(1)
	v_cvt_f32_f16_e32 v3, v7
	v_add_f32_e32 v3, v18, v3
	v_cmp_nlt_f32_e32 vcc, s23, v3
	s_and_saveexec_b64 s[6:7], vcc
	s_cbranch_execz .LBB0_409
	v_mul_f32_e32 v7, 0x3fb8aa3b, v3
	v_rndne_f32_e32 v8, v7
	v_sub_f32_e32 v9, v7, v8
	v_fma_f32 v7, v3, s19, -v7
	v_fmac_f32_e32 v7, 0x32a5705f, v3
	v_add_f32_e32 v7, v9, v7
	v_cvt_i32_f32_e32 v8, v8
	v_exp_f32_e32 v7, v7
	v_cmp_ngt_f32_e32 vcc, s96, v3
	v_ldexp_f32 v7, v7, v8
	s_nop 0
	v_cndmask_b32_e32 v7, 0, v7, vcc
	v_cmp_nlt_f32_e32 vcc, s97, v3
	s_nop 1
	v_cndmask_b32_e32 v3, v216, v7, vcc
	v_add_f32_e32 v7, 1.0, v3
	v_add_f32_e32 v8, -1.0, v7
	v_sub_f32_e32 v9, v8, v7
	v_add_f32_e32 v9, 1.0, v9
	v_sub_f32_e32 v8, v3, v8
	v_add_f32_e32 v11, v8, v9
	v_frexp_mant_f32_e32 v12, v7
	v_cvt_f64_f32_e32 v[8:9], v7
	v_frexp_exp_i32_f64_e32 v8, v[8:9]
	v_cmp_gt_f32_e32 vcc, s62, v12
	s_nop 1
	v_subbrev_co_u32_e32 v16, vcc, 0, v8, vcc
	v_sub_u32_e32 v8, 0, v16
	v_ldexp_f32 v7, v7, v8
	v_ldexp_f32 v8, v11, v8
	v_add_f32_e32 v11, -1.0, v7
	v_add_f32_e32 v9, 1.0, v11
	v_sub_f32_e32 v9, v7, v9
	v_add_f32_e32 v12, v8, v9
	v_add_f32_e32 v9, 1.0, v7
	v_add_f32_e32 v13, -1.0, v9
	v_sub_f32_e32 v7, v7, v13
	v_add_f32_e32 v7, v8, v7
	v_add_f32_e32 v22, v9, v7
	v_rcp_f32_e32 v23, v22
	v_sub_f32_e32 v8, v9, v22
	v_add_f32_e32 v9, v11, v12
	v_add_f32_e32 v7, v7, v8
	v_sub_f32_e32 v8, v11, v9
	v_mul_f32_e32 v24, v9, v23
	v_add_f32_e32 v11, v12, v8
	v_mul_f32_e32 v12, v22, v24
	v_fma_f32 v14, v24, v22, -v12
	v_fmac_f32_e32 v14, v24, v7
	v_add_f32_e32 v8, v12, v14
	v_sub_f32_e32 v13, v9, v8
	v_pk_add_f32 v[20:21], v[8:9], v[12:13] neg_lo:[0,1] neg_hi:[0,1]
	v_mov_b32_e32 v15, v8
	v_pk_add_f32 v[8:9], v[20:21], v[14:15] neg_lo:[0,1] neg_hi:[0,1]
	v_cmp_neq_f32_e32 vcc, s21, v3
	v_add_f32_e32 v9, v11, v9
	v_add_f32_e32 v8, v8, v9
	v_add_f32_e32 v9, v13, v8
	v_mul_f32_e32 v11, v23, v9
	v_mul_f32_e32 v12, v22, v11
	v_fma_f32 v14, v11, v22, -v12
	v_fmac_f32_e32 v14, v11, v7
	v_sub_f32_e32 v7, v13, v9
	v_add_f32_e32 v7, v8, v7
	v_add_f32_e32 v8, v12, v14
	v_sub_f32_e32 v13, v9, v8
	v_pk_add_f32 v[20:21], v[8:9], v[12:13] neg_lo:[0,1] neg_hi:[0,1]
	v_mov_b32_e32 v15, v8
	v_pk_add_f32 v[8:9], v[20:21], v[14:15] neg_lo:[0,1] neg_hi:[0,1]
	s_nop 0
	v_add_f32_e32 v7, v7, v9
	v_add_f32_e32 v7, v8, v7
	v_add_f32_e32 v9, v24, v11
	v_add_f32_e32 v7, v13, v7
	v_sub_f32_e32 v8, v9, v24
	v_mul_f32_e32 v7, v23, v7
	v_sub_f32_e32 v8, v11, v8
	v_add_f32_e32 v7, v8, v7
	v_add_f32_e32 v11, v9, v7
	v_mul_f32_e32 v12, v11, v11
	v_fmamk_f32 v8, v12, 0x3e9b6dac, v204
	v_fmaak_f32 v139, v12, v8, 0x3f2aaada
	v_cvt_f32_i32_e32 v8, v16
	v_sub_f32_e32 v9, v11, v9
	v_sub_f32_e32 v7, v7, v9
	v_mul_f32_e32 v9, v11, v12
	v_pk_mul_f32 v[14:15], v[8:9], v[138:139]
	v_ldexp_f32 v13, v11, 1
	v_fma_f32 v12, v8, s63, -v14
	v_fmac_f32_e32 v12, 0xb102e308, v8
	v_pk_add_f32 v[8:9], v[14:15], v[12:13]
	v_ldexp_f32 v7, v7, 1
	v_sub_f32_e32 v11, v9, v13
	v_sub_f32_e32 v11, v15, v11
	v_add_f32_e32 v21, v7, v11
	v_mov_b32_e32 v20, v14
	v_pk_add_f32 v[14:15], v[8:9], v[14:15] neg_lo:[0,1] neg_hi:[0,1]
	v_pk_add_f32 v[22:23], v[8:9], v[20:21]
	v_mov_b32_e32 v13, v8
	v_mov_b32_e32 v15, v23
	v_pk_add_f32 v[24:25], v[12:13], v[14:15] neg_lo:[0,1] neg_hi:[0,1]
	v_pk_add_f32 v[12:13], v[12:13], v[14:15]
	v_mov_b32_e32 v20, v21
	v_pk_add_f32 v[14:15], v[12:13], v[8:9] op_sel:[1,0] op_sel_hi:[0,1] neg_lo:[0,1] neg_hi:[0,1]
	v_pk_add_f32 v[26:27], v[22:23], v[14:15] op_sel_hi:[1,0] neg_lo:[0,1] neg_hi:[0,1]
	v_mov_b32_e32 v22, v23
	v_mov_b32_e32 v23, v13
	v_pk_mov_b32 v[14:15], v[8:9], v[14:15] op_sel:[1,0]
	v_mov_b32_e32 v21, v8
	v_pk_add_f32 v[14:15], v[22:23], v[14:15] neg_lo:[0,1] neg_hi:[0,1]
	v_mov_b32_e32 v26, v24
	v_pk_add_f32 v[8:9], v[20:21], v[14:15] neg_lo:[0,1] neg_hi:[0,1]
	v_mov_b32_e32 v25, v13
	v_pk_add_f32 v[14:15], v[26:27], v[8:9]
	s_nop 0
	v_pk_add_f32 v[20:21], v[14:15], v[14:15] op_sel:[0,1] op_sel_hi:[1,0]
	s_nop 0
	v_pk_add_f32 v[12:13], v[12:13], v[20:21] op_sel:[1,0] op_sel_hi:[0,1]
	v_mov_b32_e32 v15, v12
	v_pk_add_f32 v[22:23], v[14:15], v[24:25] neg_lo:[0,1] neg_hi:[0,1]
	v_mov_b32_e32 v9, v20
	v_sub_f32_e32 v7, v14, v22
	v_pk_add_f32 v[8:9], v[8:9], v[22:23] neg_lo:[0,1] neg_hi:[0,1]
	v_sub_f32_e32 v7, v24, v7
	v_add_f32_e32 v7, v8, v7
	v_add_f32_e32 v7, v7, v9
	v_add_f32_e32 v7, v12, v7
	v_cndmask_b32_e32 v7, v216, v7, vcc
	v_cmp_lt_f32_e64 vcc, |v3|, s64
	s_nop 1
	v_cndmask_b32_e32 v3, v7, v3, vcc
.LBB0_409:
	s_or_b64 exec, exec, s[6:7]
	s_waitcnt vmcnt(0)
	v_cvt_f32_f16_e32 v5, v5
	v_mul_f32_e64 v3, v3, -v4
	v_mul_f32_e32 v4, 0x3fb8aa3b, v3
	v_fma_f32 v7, v3, s19, -v4
	v_rndne_f32_e32 v8, v4
	v_fmac_f32_e32 v7, 0x32a5705f, v3
	v_sub_f32_e32 v4, v4, v8
	v_mul_f32_e32 v5, 0xbfb8aa3b, v5
	v_add_f32_e32 v4, v4, v7
	v_exp_f32_e32 v5, v5
	v_exp_f32_e32 v4, v4
	v_cvt_i32_f32_e32 v7, v8
	v_add_f32_e32 v16, v1, v2
	v_add_f32_e32 v2, 1.0, v5
	v_cmp_ngt_f32_e32 vcc, s96, v3
	v_ldexp_f32 v1, v4, v7
	v_div_scale_f32 v4, s[2:3], v2, v2, 1.0
	v_rcp_f32_e32 v5, v4
	v_cndmask_b32_e32 v1, 0, v1, vcc
	v_cmp_nlt_f32_e32 vcc, s97, v3
	s_movk_i32 s2, 0xff90
	s_nop 0
	v_cndmask_b32_e32 v14, v216, v1, vcc
	v_fma_f32 v1, -v4, v5, 1.0
	v_fmac_f32_e32 v5, v1, v5
	v_div_scale_f32 v1, vcc, 1.0, v2, 1.0
	v_mul_f32_e32 v3, v1, v5
	v_fma_f32 v7, -v4, v3, v1
	v_fmac_f32_e32 v3, v7, v5
	v_fma_f32 v1, -v4, v3, v1
	v_div_fmas_f32 v1, v1, v5, v3
	v_div_fixup_f32 v15, v1, v2, 1.0
	v_mad_u64_u32 v[0:1], s[2:3], v6, s2, v[0:1]
	v_mul_f32_e32 v15, v14, v15
	ds_write_b128 v0, v[14:17] offset:49152

; __device__ __forceinline__ float red16(float x) { x = red8(x); x += dppf<0x140>(x); return x; }
; __device__ __forceinline__ void gdn_group8(float (&S)[4], float (&pp)[16], int j0, const LAS float* L, int sbase_, int kg, int vl) {
;     ...
;     for (int j = 0; j < 8; ++j) {
;         const f32x2 k0 = (f32x2){k[j][0], k[j][1]}, k1 = (f32x2){k[j][2], k[j][3]};
;         f32x2 r2 = s0 * k0; r2 = s1 * k1 + r2;
;         const float r = red16(r2.x + r2.y);
;         const float u = sc[j][1] * (v[j] - sc[j][0] * r);
;         const f32x2 uu = (f32x2){u, u}, aa = (f32x2){sc[j][0], sc[j][0]};
;         s0 = s0 * aa + k0 * uu; s1 = s1 * aa + k1 * uu;
;         f32x2 p2 = s0 * (f32x2){q[j][0], q[j][1]}; p2 = s1 * (f32x2){q[j][2], q[j][3]} + p2;
;         pp[j0 + j] = p2.x + p2.y;
;     }
.Lgdn_step_loop:
	s_waitcnt lgkmcnt(0)
	v_pk_mul_f32 v[158:159], v[10:11], v[32:33]
	v_pk_mul_f32 v[160:161], v[10:11], v[64:65] op_sel_hi:[1,0]
	v_pk_fma_f32 v[158:159], v[12:13], v[34:35], v[158:159]
	v_pk_mul_f32 v[162:163], v[12:13], v[64:65] op_sel_hi:[1,0]
	v_add_f32_e32 v168, v158, v159
	ds_read2_b32 v[104:105], v173 offset1:32
	ds_read2_b32 v[106:107], v173 offset0:64 offset1:96
	v_add_f32_dpp v168, v168, v168 quad_perm:[1,0,3,2] row_mask:0xf bank_mask:0xf bound_ctrl:1
	ds_read_b128 v[72:75], v172 offset:1024
	ds_read_b128 v[76:79], v172 offset:17408
	v_add_f32_dpp v168, v168, v168 quad_perm:[2,3,0,1] row_mask:0xf bank_mask:0xf bound_ctrl:1
	ds_read_b128 v[80:83], v172 offset:1280
	ds_read_b128 v[84:87], v172 offset:17664
	v_add_f32_dpp v168, v168, v168 row_half_mirror row_mask:0xf bank_mask:0xf bound_ctrl:1
	ds_read_b128 v[88:91], v172 offset:1536
	ds_read_b128 v[92:95], v172 offset:17920
	v_add_f32_dpp v168, v168, v168 row_mirror row_mask:0xf bank_mask:0xf bound_ctrl:1
	v_fma_f32 v170, -v65, v168, v60
	v_pk_fma_f32 v[10:11], v[32:33], v[170:171], v[160:161] op_sel_hi:[1,0,1]
	v_pk_fma_f32 v[12:13], v[34:35], v[170:171], v[162:163] op_sel_hi:[1,0,1]
	v_pk_mul_f32 v[158:159], v[10:11], v[40:41]
	v_pk_mul_f32 v[160:161], v[10:11], v[66:67] op_sel_hi:[1,0]
	v_pk_fma_f32 v[158:159], v[12:13], v[42:43], v[158:159]
	v_pk_mul_f32 v[162:163], v[12:13], v[66:67] op_sel_hi:[1,0]
	v_add_f32_e32 v168, v158, v159
	v_pk_mul_f32 v[164:165], v[28:29], v[10:11]
	ds_read_b128 v[96:99], v172 offset:1792
	v_add_f32_dpp v168, v168, v168 quad_perm:[1,0,3,2] row_mask:0xf bank_mask:0xf bound_ctrl:1
	v_pk_fma_f32 v[164:165], v[30:31], v[12:13], v[164:165]
	ds_read_b128 v[100:103], v172 offset:18176
	v_add_f32_dpp v168, v168, v168 quad_perm:[2,3,0,1] row_mask:0xf bank_mask:0xf bound_ctrl:1
	v_add_f32_e32 v116, v164, v165
	ds_read2_b64 v[108:111], v174 offset0:8 offset1:10
	v_add_f32_dpp v168, v168, v168 row_half_mirror row_mask:0xf bank_mask:0xf bound_ctrl:1
	ds_read2_b64 v[112:115], v174 offset0:12 offset1:14
	v_add_u32_e32 v173, 0x200, v173
	v_add_f32_dpp v168, v168, v168 row_mirror row_mask:0xf bank_mask:0xf bound_ctrl:1
	v_fma_f32 v170, -v67, v168, v61
	v_pk_fma_f32 v[10:11], v[40:41], v[170:171], v[160:161] op_sel_hi:[1,0,1]
	v_pk_fma_f32 v[12:13], v[42:43], v[170:171], v[162:163] op_sel_hi:[1,0,1]
	v_pk_mul_f32 v[158:159], v[10:11], v[48:49]
	v_pk_mul_f32 v[160:161], v[10:11], v[68:69] op_sel_hi:[1,0]
	v_pk_fma_f32 v[158:159], v[12:13], v[50:51], v[158:159]
	v_pk_mul_f32 v[162:163], v[12:13], v[68:69] op_sel_hi:[1,0]
	v_add_f32_e32 v168, v158, v159
	v_pk_mul_f32 v[166:167], v[36:37], v[10:11]
	v_add_f32_dpp v140, v116, v116 row_mirror row_mask:0xf bank_mask:0x3 bound_ctrl:1
	v_add_f32_dpp v168, v168, v168 quad_perm:[1,0,3,2] row_mask:0xf bank_mask:0xf bound_ctrl:1
	v_pk_fma_f32 v[166:167], v[38:39], v[12:13], v[166:167]
	s_add_i32 s8, s8, -1
	v_add_f32_dpp v168, v168, v168 quad_perm:[2,3,0,1] row_mask:0xf bank_mask:0xf bound_ctrl:1
	v_add_f32_e32 v117, v166, v167
	s_nop 0
	v_add_f32_dpp v168, v168, v168 row_half_mirror row_mask:0xf bank_mask:0xf bound_ctrl:1
	v_add_f32_dpp v140, v117, v117 row_mirror row_mask:0xf bank_mask:0xc bound_ctrl:1
	s_nop 0
	v_add_f32_dpp v168, v168, v168 row_mirror row_mask:0xf bank_mask:0xf bound_ctrl:1
	v_fma_f32 v170, -v69, v168, v62
	v_pk_fma_f32 v[10:11], v[48:49], v[170:171], v[160:161] op_sel_hi:[1,0,1]
	v_pk_fma_f32 v[12:13], v[50:51], v[170:171], v[162:163] op_sel_hi:[1,0,1]
	v_pk_mul_f32 v[158:159], v[10:11], v[56:57]
	v_pk_mul_f32 v[160:161], v[10:11], v[70:71] op_sel_hi:[1,0]
	v_pk_fma_f32 v[158:159], v[12:13], v[58:59], v[158:159]
	v_pk_mul_f32 v[162:163], v[12:13], v[70:71] op_sel_hi:[1,0]
	v_add_f32_e32 v168, v158, v159
	v_pk_mul_f32 v[164:165], v[44:45], v[10:11]
	v_add_f32_dpp v148, v140, v140 row_half_mirror row_mask:0xf bank_mask:0x5 bound_ctrl:1
	v_add_f32_dpp v168, v168, v168 quad_perm:[1,0,3,2] row_mask:0xf bank_mask:0xf bound_ctrl:1
	v_pk_fma_f32 v[164:165], v[46:47], v[12:13], v[164:165]
	s_nop 0
	v_add_f32_dpp v168, v168, v168 quad_perm:[2,3,0,1] row_mask:0xf bank_mask:0xf bound_ctrl:1
	v_add_f32_e32 v118, v164, v165
	s_nop 0
	v_add_f32_dpp v168, v168, v168 row_half_mirror row_mask:0xf bank_mask:0xf bound_ctrl:1
	v_add_f32_dpp v141, v118, v118 row_mirror row_mask:0xf bank_mask:0x3 bound_ctrl:1
	s_nop 0
	v_add_f32_dpp v168, v168, v168 row_mirror row_mask:0xf bank_mask:0xf bound_ctrl:1
	v_fma_f32 v170, -v71, v168, v63
	v_pk_fma_f32 v[10:11], v[56:57], v[170:171], v[160:161] op_sel_hi:[1,0,1]
	v_pk_fma_f32 v[12:13], v[58:59], v[170:171], v[162:163] op_sel_hi:[1,0,1]
	s_waitcnt lgkmcnt(0)
; template <int CTRL> __device__ __forceinline__ float dppf(float x) { return __builtin_bit_cast(float, __builtin_amdgcn_update_dpp(0, __builtin_bit_cast(int, x), CTRL, 0xF, 0xF, true)); }
; __device__ __forceinline__ float red16(float x) { x = red8(x); x += dppf<0x140>(x); return x; }
; __device__ __forceinline__ void gdn_group8(float (&S)[4], float (&pp)[16], int j0, const LAS float* L, int sbase_, int kg, int vl) {
;     ...
;     for (int j = 0; j < 8; ++j) {
;         const f32x2 k0 = (f32x2){k[j][0], k[j][1]}, k1 = (f32x2){k[j][2], k[j][3]};
;         f32x2 r2 = s0 * k0; r2 = s1 * k1 + r2;
;         const float r = red16(r2.x + r2.y);
;         const float u = sc[j][1] * (v[j] - sc[j][0] * r);
;         const f32x2 uu = (f32x2){u, u}, aa = (f32x2){sc[j][0], sc[j][0]};
;         s0 = s0 * aa + k0 * uu; s1 = s1 * aa + k1 * uu;
;         f32x2 p2 = s0 * (f32x2){q[j][0], q[j][1]}; p2 = s1 * (f32x2){q[j][2], q[j][3]} + p2;
;         pp[j0 + j] = p2.x + p2.y;
;     }
; __device__ __forceinline__ float reduce_scatter16(const float (&p)[16], int kg) {
;     const bool b3 = kg & 8, b2 = kg & 4, b1 = kg & 2, b0 = kg & 1;
;     float t[8], u[4], w[2];
; #pragma unroll
;     for (int j = 0; j < 8; ++j) { const float keep = b3 ? p[j + 8] : p[j], send = b3 ? p[j] : p[j + 8]; t[j] = keep + dppf<0x140>(send); }
; #pragma unroll
;     for (int j = 0; j < 4; ++j) { const float keep = b2 ? t[j + 4] : t[j], send = b2 ? t[j] : t[j + 4]; u[j] = keep + dppf<0x141>(send); }
; #pragma unroll
;     for (int j = 0; j < 2; ++j) { const float keep = b1 ? u[j + 2] : u[j], send = b1 ? u[j] : u[j + 2]; w[j] = keep + dppf<0x1B>(send); }
	v_pk_mul_f32 v[158:159], v[10:11], v[76:77]
	v_pk_mul_f32 v[160:161], v[10:11], v[108:109] op_sel_hi:[1,0]
	v_pk_fma_f32 v[158:159], v[12:13], v[78:79], v[158:159]
	v_pk_mul_f32 v[162:163], v[12:13], v[108:109] op_sel_hi:[1,0]
	v_add_f32_e32 v168, v158, v159
	v_pk_mul_f32 v[166:167], v[52:53], v[10:11]
	s_nop 0
	v_add_f32_dpp v168, v168, v168 quad_perm:[1,0,3,2] row_mask:0xf bank_mask:0xf bound_ctrl:1
	v_pk_fma_f32 v[166:167], v[54:55], v[12:13], v[166:167]
	ds_read2_b32 v[60:61], v173 offset1:32
	v_add_f32_dpp v168, v168, v168 quad_perm:[2,3,0,1] row_mask:0xf bank_mask:0xf bound_ctrl:1
	v_add_f32_e32 v119, v166, v167
	ds_read2_b32 v[62:63], v173 offset0:64 offset1:96
	v_add_f32_dpp v168, v168, v168 row_half_mirror row_mask:0xf bank_mask:0xf bound_ctrl:1
	ds_read_b128 v[28:31], v172 offset:2048
	ds_read_b128 v[32:35], v172 offset:18432
	v_add_f32_dpp v168, v168, v168 row_mirror row_mask:0xf bank_mask:0xf bound_ctrl:1
	v_fma_f32 v170, -v109, v168, v104
	v_pk_fma_f32 v[10:11], v[76:77], v[170:171], v[160:161] op_sel_hi:[1,0,1]
	v_pk_fma_f32 v[12:13], v[78:79], v[170:171], v[162:163] op_sel_hi:[1,0,1]
	v_pk_mul_f32 v[158:159], v[10:11], v[84:85]
	v_pk_mul_f32 v[160:161], v[10:11], v[110:111] op_sel_hi:[1,0]
	v_pk_fma_f32 v[158:159], v[12:13], v[86:87], v[158:159]
	v_pk_mul_f32 v[162:163], v[12:13], v[110:111] op_sel_hi:[1,0]
	v_add_f32_e32 v168, v158, v159
	v_pk_mul_f32 v[164:165], v[72:73], v[10:11]
	ds_read_b128 v[36:39], v172 offset:2304
	v_add_f32_dpp v168, v168, v168 quad_perm:[1,0,3,2] row_mask:0xf bank_mask:0xf bound_ctrl:1
	v_pk_fma_f32 v[164:165], v[74:75], v[12:13], v[164:165]
	ds_read_b128 v[40:43], v172 offset:18688
	v_add_f32_dpp v168, v168, v168 quad_perm:[2,3,0,1] row_mask:0xf bank_mask:0xf bound_ctrl:1
	v_add_f32_e32 v120, v164, v165
	ds_read_b128 v[44:47], v172 offset:2560
	v_add_f32_dpp v168, v168, v168 row_half_mirror row_mask:0xf bank_mask:0xf bound_ctrl:1
	ds_read_b128 v[48:51], v172 offset:18944
	ds_read_b128 v[52:55], v172 offset:2816
	v_add_f32_dpp v168, v168, v168 row_mirror row_mask:0xf bank_mask:0xf bound_ctrl:1
	v_fma_f32 v170, -v111, v168, v105
	v_pk_fma_f32 v[10:11], v[84:85], v[170:171], v[160:161] op_sel_hi:[1,0,1]
	v_pk_fma_f32 v[12:13], v[86:87], v[170:171], v[162:163] op_sel_hi:[1,0,1]
	v_pk_mul_f32 v[158:159], v[10:11], v[92:93]
	v_pk_mul_f32 v[160:161], v[10:11], v[112:113] op_sel_hi:[1,0]
	v_pk_fma_f32 v[158:159], v[12:13], v[94:95], v[158:159]
	v_pk_mul_f32 v[162:163], v[12:13], v[112:113] op_sel_hi:[1,0]
	v_add_f32_e32 v168, v158, v159
	v_pk_mul_f32 v[166:167], v[80:81], v[10:11]
	ds_read_b128 v[56:59], v172 offset:19200
	v_add_f32_dpp v168, v168, v168 quad_perm:[1,0,3,2] row_mask:0xf bank_mask:0xf bound_ctrl:1
	v_pk_fma_f32 v[166:167], v[82:83], v[12:13], v[166:167]
	ds_read2_b64 v[64:67], v174 offset0:16 offset1:18
	v_add_f32_dpp v168, v168, v168 quad_perm:[2,3,0,1] row_mask:0xf bank_mask:0xf bound_ctrl:1
	v_add_f32_e32 v121, v166, v167
	ds_read2_b64 v[68:71], v174 offset0:20 offset1:22
	v_add_f32_dpp v168, v168, v168 row_half_mirror row_mask:0xf bank_mask:0xf bound_ctrl:1
	v_add_u32_e32 v173, 0x200, v173
	v_add_f32_dpp v142, v120, v120 row_mirror row_mask:0xf bank_mask:0x3 bound_ctrl:1
	v_add_f32_dpp v168, v168, v168 row_mirror row_mask:0xf bank_mask:0xf bound_ctrl:1
	v_fma_f32 v170, -v113, v168, v106
	v_pk_fma_f32 v[10:11], v[92:93], v[170:171], v[160:161] op_sel_hi:[1,0,1]
	v_pk_fma_f32 v[12:13], v[94:95], v[170:171], v[162:163] op_sel_hi:[1,0,1]
	v_pk_mul_f32 v[158:159], v[10:11], v[100:101]
	v_pk_mul_f32 v[160:161], v[10:11], v[114:115] op_sel_hi:[1,0]
	v_pk_fma_f32 v[158:159], v[12:13], v[102:103], v[158:159]
	v_pk_mul_f32 v[162:163], v[12:13], v[114:115] op_sel_hi:[1,0]
	v_add_f32_e32 v168, v158, v159
	v_pk_mul_f32 v[164:165], v[88:89], v[10:11]
	v_add_f32_dpp v142, v121, v121 row_mirror row_mask:0xf bank_mask:0xc bound_ctrl:1
	v_add_f32_dpp v168, v168, v168 quad_perm:[1,0,3,2] row_mask:0xf bank_mask:0xf bound_ctrl:1
	v_pk_fma_f32 v[164:165], v[90:91], v[12:13], v[164:165]
	v_add_f32_dpp v141, v119, v119 row_mirror row_mask:0xf bank_mask:0xc bound_ctrl:1
	v_add_f32_dpp v168, v168, v168 quad_perm:[2,3,0,1] row_mask:0xf bank_mask:0xf bound_ctrl:1
	v_add_f32_e32 v122, v164, v165
	v_add_f32_dpp v149, v142, v142 row_half_mirror row_mask:0xf bank_mask:0x5 bound_ctrl:1
	v_add_f32_dpp v168, v168, v168 row_half_mirror row_mask:0xf bank_mask:0xf bound_ctrl:1
	v_add_f32_dpp v143, v122, v122 row_mirror row_mask:0xf bank_mask:0x3 bound_ctrl:1
	v_add_f32_dpp v148, v141, v141 row_half_mirror row_mask:0xf bank_mask:0xa bound_ctrl:1
	v_add_f32_dpp v168, v168, v168 row_mirror row_mask:0xf bank_mask:0xf bound_ctrl:1
	v_fma_f32 v170, -v115, v168, v107
	v_pk_fma_f32 v[10:11], v[100:101], v[170:171], v[160:161] op_sel_hi:[1,0,1]
	v_pk_fma_f32 v[12:13], v[102:103], v[170:171], v[162:163] op_sel_hi:[1,0,1]
	s_waitcnt lgkmcnt(0)
; template <int CTRL> __device__ __forceinline__ float dppf(float x) { return __builtin_bit_cast(float, __builtin_amdgcn_update_dpp(0, __builtin_bit_cast(int, x), CTRL, 0xF, 0xF, true)); }
; __device__ __forceinline__ float red16(float x) { x = red8(x); x += dppf<0x140>(x); return x; }
; __device__ __forceinline__ void gdn_group8(float (&S)[4], float (&pp)[16], int j0, const LAS float* L, int sbase_, int kg, int vl) {
;     ...
;     for (int j = 0; j < 8; ++j) {
;         const f32x2 k0 = (f32x2){k[j][0], k[j][1]}, k1 = (f32x2){k[j][2], k[j][3]};
;         f32x2 r2 = s0 * k0; r2 = s1 * k1 + r2;
;         const float r = red16(r2.x + r2.y);
;         const float u = sc[j][1] * (v[j] - sc[j][0] * r);
;         const f32x2 uu = (f32x2){u, u}, aa = (f32x2){sc[j][0], sc[j][0]};
;         s0 = s0 * aa + k0 * uu; s1 = s1 * aa + k1 * uu;
;         f32x2 p2 = s0 * (f32x2){q[j][0], q[j][1]}; p2 = s1 * (f32x2){q[j][2], q[j][3]} + p2;
;         pp[j0 + j] = p2.x + p2.y;
;     }
; __device__ __forceinline__ float reduce_scatter16(const float (&p)[16], int kg) {
;     const bool b3 = kg & 8, b2 = kg & 4, b1 = kg & 2, b0 = kg & 1;
;     float t[8], u[4], w[2];
; #pragma unroll
;     for (int j = 0; j < 8; ++j) { const float keep = b3 ? p[j + 8] : p[j], send = b3 ? p[j] : p[j + 8]; t[j] = keep + dppf<0x140>(send); }
; #pragma unroll
;     for (int j = 0; j < 4; ++j) { const float keep = b2 ? t[j + 4] : t[j], send = b2 ? t[j] : t[j + 4]; u[j] = keep + dppf<0x141>(send); }
; #pragma unroll
;     for (int j = 0; j < 2; ++j) { const float keep = b1 ? u[j + 2] : u[j], send = b1 ? u[j] : u[j + 2]; w[j] = keep + dppf<0x1B>(send); }
	v_pk_mul_f32 v[158:159], v[10:11], v[32:33]
	v_pk_mul_f32 v[160:161], v[10:11], v[64:65] op_sel_hi:[1,0]
	v_pk_fma_f32 v[158:159], v[12:13], v[34:35], v[158:159]
	v_pk_mul_f32 v[162:163], v[12:13], v[64:65] op_sel_hi:[1,0]
	v_add_f32_e32 v168, v158, v159
	v_pk_mul_f32 v[166:167], v[96:97], v[10:11]
	s_nop 0
	v_add_f32_dpp v168, v168, v168 quad_perm:[1,0,3,2] row_mask:0xf bank_mask:0xf bound_ctrl:1
	v_pk_fma_f32 v[166:167], v[98:99], v[12:13], v[166:167]
	ds_read2_b32 v[104:105], v173 offset1:32
	v_add_f32_dpp v168, v168, v168 quad_perm:[2,3,0,1] row_mask:0xf bank_mask:0xf bound_ctrl:1
	v_add_f32_e32 v123, v166, v167
	ds_read2_b32 v[106:107], v173 offset0:64 offset1:96
	v_add_f32_dpp v168, v168, v168 row_half_mirror row_mask:0xf bank_mask:0xf bound_ctrl:1
	ds_read_b128 v[72:75], v172 offset:3072
	ds_read_b128 v[76:79], v172 offset:19456
	v_add_f32_dpp v168, v168, v168 row_mirror row_mask:0xf bank_mask:0xf bound_ctrl:1
	v_fma_f32 v170, -v65, v168, v60
	v_pk_fma_f32 v[10:11], v[32:33], v[170:171], v[160:161] op_sel_hi:[1,0,1]
	v_pk_fma_f32 v[12:13], v[34:35], v[170:171], v[162:163] op_sel_hi:[1,0,1]
	v_pk_mul_f32 v[158:159], v[10:11], v[40:41]
	v_pk_mul_f32 v[160:161], v[10:11], v[66:67] op_sel_hi:[1,0]
	v_pk_fma_f32 v[158:159], v[12:13], v[42:43], v[158:159]
	v_pk_mul_f32 v[162:163], v[12:13], v[66:67] op_sel_hi:[1,0]
	v_add_f32_e32 v168, v158, v159
	v_pk_mul_f32 v[164:165], v[28:29], v[10:11]
	ds_read_b128 v[80:83], v172 offset:3328
	v_add_f32_dpp v168, v168, v168 quad_perm:[1,0,3,2] row_mask:0xf bank_mask:0xf bound_ctrl:1
	v_pk_fma_f32 v[164:165], v[30:31], v[12:13], v[164:165]
	ds_read_b128 v[84:87], v172 offset:19712
	v_add_f32_dpp v168, v168, v168 quad_perm:[2,3,0,1] row_mask:0xf bank_mask:0xf bound_ctrl:1
	v_add_f32_e32 v124, v164, v165
	ds_read_b128 v[88:91], v172 offset:3584
	v_add_f32_dpp v168, v168, v168 row_half_mirror row_mask:0xf bank_mask:0xf bound_ctrl:1
	ds_read_b128 v[92:95], v172 offset:19968
	ds_read_b128 v[96:99], v172 offset:3840
	v_add_f32_dpp v168, v168, v168 row_mirror row_mask:0xf bank_mask:0xf bound_ctrl:1
	v_fma_f32 v170, -v67, v168, v61
	v_pk_fma_f32 v[10:11], v[40:41], v[170:171], v[160:161] op_sel_hi:[1,0,1]
	v_pk_fma_f32 v[12:13], v[42:43], v[170:171], v[162:163] op_sel_hi:[1,0,1]
	v_pk_mul_f32 v[158:159], v[10:11], v[48:49]
	v_pk_mul_f32 v[160:161], v[10:11], v[68:69] op_sel_hi:[1,0]
	v_pk_fma_f32 v[158:159], v[12:13], v[50:51], v[158:159]
	v_pk_mul_f32 v[162:163], v[12:13], v[68:69] op_sel_hi:[1,0]
	v_add_f32_e32 v168, v158, v159
	v_pk_mul_f32 v[166:167], v[36:37], v[10:11]
	ds_read_b128 v[100:103], v172 offset:20224
	v_add_f32_dpp v168, v168, v168 quad_perm:[1,0,3,2] row_mask:0xf bank_mask:0xf bound_ctrl:1
	v_pk_fma_f32 v[166:167], v[38:39], v[12:13], v[166:167]
	ds_read2_b64 v[108:111], v174 offset0:24 offset1:26
	v_add_f32_dpp v168, v168, v168 quad_perm:[2,3,0,1] row_mask:0xf bank_mask:0xf bound_ctrl:1
	v_add_f32_e32 v125, v166, v167
	ds_read2_b64 v[112:115], v174 offset0:28 offset1:30
	v_add_f32_dpp v168, v168, v168 row_half_mirror row_mask:0xf bank_mask:0xf bound_ctrl:1
	v_add_u32_e32 v173, 0x200, v173
	v_add_f32_dpp v144, v124, v124 row_mirror row_mask:0xf bank_mask:0x3 bound_ctrl:1
	v_add_f32_dpp v168, v168, v168 row_mirror row_mask:0xf bank_mask:0xf bound_ctrl:1
	v_fma_f32 v170, -v69, v168, v62
	v_pk_fma_f32 v[10:11], v[48:49], v[170:171], v[160:161] op_sel_hi:[1,0,1]
	v_pk_fma_f32 v[12:13], v[50:51], v[170:171], v[162:163] op_sel_hi:[1,0,1]
	v_pk_mul_f32 v[158:159], v[10:11], v[56:57]
	v_pk_mul_f32 v[160:161], v[10:11], v[70:71] op_sel_hi:[1,0]
	v_pk_fma_f32 v[158:159], v[12:13], v[58:59], v[158:159]
	v_pk_mul_f32 v[162:163], v[12:13], v[70:71] op_sel_hi:[1,0]
	v_add_f32_e32 v168, v158, v159
	v_pk_mul_f32 v[164:165], v[44:45], v[10:11]
	v_add_f32_dpp v143, v123, v123 row_mirror row_mask:0xf bank_mask:0xc bound_ctrl:1
	v_add_f32_dpp v168, v168, v168 quad_perm:[1,0,3,2] row_mask:0xf bank_mask:0xf bound_ctrl:1
	v_pk_fma_f32 v[164:165], v[46:47], v[12:13], v[164:165]
	v_add_f32_dpp v144, v125, v125 row_mirror row_mask:0xf bank_mask:0xc bound_ctrl:1
	v_add_f32_dpp v168, v168, v168 quad_perm:[2,3,0,1] row_mask:0xf bank_mask:0xf bound_ctrl:1
	v_add_f32_e32 v126, v164, v165
	v_add_f32_dpp v149, v143, v143 row_half_mirror row_mask:0xf bank_mask:0xa bound_ctrl:1
	v_add_f32_dpp v168, v168, v168 row_half_mirror row_mask:0xf bank_mask:0xf bound_ctrl:1
	v_add_f32_dpp v145, v126, v126 row_mirror row_mask:0xf bank_mask:0x3 bound_ctrl:1
	v_cndmask_b32_e64 v154, v149, v148, s[48:49]
	v_add_f32_dpp v168, v168, v168 row_mirror row_mask:0xf bank_mask:0xf bound_ctrl:1
	v_fma_f32 v170, -v71, v168, v63
	v_pk_fma_f32 v[10:11], v[56:57], v[170:171], v[160:161] op_sel_hi:[1,0,1]
	v_pk_fma_f32 v[12:13], v[58:59], v[170:171], v[162:163] op_sel_hi:[1,0,1]
	s_waitcnt lgkmcnt(0)
; template <int CTRL> __device__ __forceinline__ float dppf(float x) { return __builtin_bit_cast(float, __builtin_amdgcn_update_dpp(0, __builtin_bit_cast(int, x), CTRL, 0xF, 0xF, true)); }
; __device__ __forceinline__ float red16(float x) { x = red8(x); x += dppf<0x140>(x); return x; }
; __device__ __forceinline__ void gdn_group8(float (&S)[4], float (&pp)[16], int j0, const LAS float* L, int sbase_, int kg, int vl) {
;     ...
;     for (int j = 0; j < 8; ++j) {
;         const f32x2 k0 = (f32x2){k[j][0], k[j][1]}, k1 = (f32x2){k[j][2], k[j][3]};
;         f32x2 r2 = s0 * k0; r2 = s1 * k1 + r2;
;         const float r = red16(r2.x + r2.y);
;         const float u = sc[j][1] * (v[j] - sc[j][0] * r);
;         const f32x2 uu = (f32x2){u, u}, aa = (f32x2){sc[j][0], sc[j][0]};
;         s0 = s0 * aa + k0 * uu; s1 = s1 * aa + k1 * uu;
;         f32x2 p2 = s0 * (f32x2){q[j][0], q[j][1]}; p2 = s1 * (f32x2){q[j][2], q[j][3]} + p2;
;         pp[j0 + j] = p2.x + p2.y;
;     }
; __device__ __forceinline__ float reduce_scatter16(const float (&p)[16], int kg) {
;     const bool b3 = kg & 8, b2 = kg & 4, b1 = kg & 2, b0 = kg & 1;
;     float t[8], u[4], w[2];
; #pragma unroll
;     for (int j = 0; j < 8; ++j) { const float keep = b3 ? p[j + 8] : p[j], send = b3 ? p[j] : p[j + 8]; t[j] = keep + dppf<0x140>(send); }
; #pragma unroll
;     for (int j = 0; j < 4; ++j) { const float keep = b2 ? t[j + 4] : t[j], send = b2 ? t[j] : t[j + 4]; u[j] = keep + dppf<0x141>(send); }
; #pragma unroll
;     for (int j = 0; j < 2; ++j) { const float keep = b1 ? u[j + 2] : u[j], send = b1 ? u[j] : u[j + 2]; w[j] = keep + dppf<0x1B>(send); }
;     const float keep = b0 ? w[1] : w[0], send = b0 ? w[0] : w[1];
;     return keep + dppf<0xB1>(send);
; }
;     ...
;                 Lc[C::OFF_O + (g * 16 + kg) * 32 + vl] = reduce_scatter16(pp, kg); }
	v_pk_mul_f32 v[158:159], v[10:11], v[76:77]
	v_pk_mul_f32 v[160:161], v[10:11], v[108:109] op_sel_hi:[1,0]
	v_pk_fma_f32 v[158:159], v[12:13], v[78:79], v[158:159]
	v_pk_mul_f32 v[162:163], v[12:13], v[108:109] op_sel_hi:[1,0]
	v_add_f32_e32 v168, v158, v159
	v_pk_mul_f32 v[166:167], v[52:53], v[10:11]
	v_cndmask_b32_e64 v155, v148, v149, s[48:49]
	v_add_f32_dpp v168, v168, v168 quad_perm:[1,0,3,2] row_mask:0xf bank_mask:0xf bound_ctrl:1
	v_pk_fma_f32 v[166:167], v[54:55], v[12:13], v[166:167]
	ds_read_b128 v[28:31], v172 offset:4096
	v_add_f32_dpp v168, v168, v168 quad_perm:[2,3,0,1] row_mask:0xf bank_mask:0xf bound_ctrl:1
	v_add_f32_e32 v127, v166, v167
	ds_read_b128 v[32:35], v172 offset:20480
	v_add_f32_dpp v168, v168, v168 row_half_mirror row_mask:0xf bank_mask:0xf bound_ctrl:1
	ds_read_b128 v[36:39], v172 offset:4352
	ds_read_b128 v[40:43], v172 offset:20736
	v_add_f32_dpp v168, v168, v168 row_mirror row_mask:0xf bank_mask:0xf bound_ctrl:1
	v_fma_f32 v170, -v109, v168, v104
	v_pk_fma_f32 v[10:11], v[76:77], v[170:171], v[160:161] op_sel_hi:[1,0,1]
	v_pk_fma_f32 v[12:13], v[78:79], v[170:171], v[162:163] op_sel_hi:[1,0,1]
	v_pk_mul_f32 v[158:159], v[10:11], v[84:85]
	v_pk_mul_f32 v[160:161], v[10:11], v[110:111] op_sel_hi:[1,0]
	v_pk_fma_f32 v[158:159], v[12:13], v[86:87], v[158:159]
	v_pk_mul_f32 v[162:163], v[12:13], v[110:111] op_sel_hi:[1,0]
	v_add_f32_e32 v168, v158, v159
	v_pk_mul_f32 v[164:165], v[72:73], v[10:11]
	ds_read_b128 v[44:47], v172 offset:4608
	v_add_f32_dpp v168, v168, v168 quad_perm:[1,0,3,2] row_mask:0xf bank_mask:0xf bound_ctrl:1
	v_pk_fma_f32 v[164:165], v[74:75], v[12:13], v[164:165]
	ds_read_b128 v[48:51], v172 offset:20992
	v_add_f32_dpp v168, v168, v168 quad_perm:[2,3,0,1] row_mask:0xf bank_mask:0xf bound_ctrl:1
	v_add_f32_e32 v128, v164, v165
	ds_read_b128 v[52:55], v172 offset:4864
	v_add_f32_dpp v168, v168, v168 row_half_mirror row_mask:0xf bank_mask:0xf bound_ctrl:1
	ds_read_b128 v[56:59], v172 offset:21248
	ds_read2_b32 v[60:61], v173 offset1:32
	v_add_f32_dpp v168, v168, v168 row_mirror row_mask:0xf bank_mask:0xf bound_ctrl:1
	v_fma_f32 v170, -v111, v168, v105
	v_pk_fma_f32 v[10:11], v[84:85], v[170:171], v[160:161] op_sel_hi:[1,0,1]
	v_pk_fma_f32 v[12:13], v[86:87], v[170:171], v[162:163] op_sel_hi:[1,0,1]
	v_pk_mul_f32 v[158:159], v[10:11], v[92:93]
	v_pk_mul_f32 v[160:161], v[10:11], v[112:113] op_sel_hi:[1,0]
	v_pk_fma_f32 v[158:159], v[12:13], v[94:95], v[158:159]
	v_pk_mul_f32 v[162:163], v[12:13], v[112:113] op_sel_hi:[1,0]
	v_add_f32_e32 v168, v158, v159
	v_pk_mul_f32 v[166:167], v[80:81], v[10:11]
	ds_read2_b32 v[62:63], v173 offset0:64 offset1:96
	v_add_f32_dpp v168, v168, v168 quad_perm:[1,0,3,2] row_mask:0xf bank_mask:0xf bound_ctrl:1
	v_pk_fma_f32 v[166:167], v[82:83], v[12:13], v[166:167]
	ds_read2_b64 v[64:67], v174 offset0:32 offset1:34
	v_add_f32_dpp v168, v168, v168 quad_perm:[2,3,0,1] row_mask:0xf bank_mask:0xf bound_ctrl:1
	v_add_f32_e32 v129, v166, v167
	ds_read2_b64 v[68:71], v174 offset0:36 offset1:38
	v_add_f32_dpp v168, v168, v168 row_half_mirror row_mask:0xf bank_mask:0xf bound_ctrl:1
	v_add_u32_e32 v173, 0x200, v173
	v_add_u32_e32 v172, 0x1000, v172
	v_add_f32_dpp v168, v168, v168 row_mirror row_mask:0xf bank_mask:0xf bound_ctrl:1
	v_fma_f32 v170, -v113, v168, v106
	v_pk_fma_f32 v[10:11], v[92:93], v[170:171], v[160:161] op_sel_hi:[1,0,1]
	v_pk_fma_f32 v[12:13], v[94:95], v[170:171], v[162:163] op_sel_hi:[1,0,1]
	v_pk_mul_f32 v[158:159], v[10:11], v[100:101]
	v_pk_mul_f32 v[160:161], v[10:11], v[114:115] op_sel_hi:[1,0]
	v_pk_fma_f32 v[158:159], v[12:13], v[102:103], v[158:159]
	v_pk_mul_f32 v[162:163], v[12:13], v[114:115] op_sel_hi:[1,0]
	v_add_f32_e32 v168, v158, v159
	v_pk_mul_f32 v[164:165], v[88:89], v[10:11]
	v_add_u32_e32 v174, 0x100, v174
	v_add_f32_dpp v168, v168, v168 quad_perm:[1,0,3,2] row_mask:0xf bank_mask:0xf bound_ctrl:1
	v_pk_fma_f32 v[164:165], v[90:91], v[12:13], v[164:165]
	v_add_f32_dpp v146, v128, v128 row_mirror row_mask:0xf bank_mask:0x3 bound_ctrl:1
	v_add_f32_dpp v168, v168, v168 quad_perm:[2,3,0,1] row_mask:0xf bank_mask:0xf bound_ctrl:1
	v_add_f32_e32 v130, v164, v165
	v_add_f32_dpp v146, v129, v129 row_mirror row_mask:0xf bank_mask:0xc bound_ctrl:1
	v_add_f32_dpp v168, v168, v168 row_half_mirror row_mask:0xf bank_mask:0xf bound_ctrl:1
	v_add_f32_dpp v147, v130, v130 row_mirror row_mask:0xf bank_mask:0x3 bound_ctrl:1
	v_add_f32_dpp v145, v127, v127 row_mirror row_mask:0xf bank_mask:0xc bound_ctrl:1
	v_add_f32_dpp v168, v168, v168 row_mirror row_mask:0xf bank_mask:0xf bound_ctrl:1
	v_fma_f32 v170, -v115, v168, v107
	v_pk_fma_f32 v[10:11], v[100:101], v[170:171], v[160:161] op_sel_hi:[1,0,1]
	v_pk_fma_f32 v[12:13], v[102:103], v[170:171], v[162:163] op_sel_hi:[1,0,1]
	v_pk_mul_f32 v[166:167], v[96:97], v[10:11]
	v_add_f32_dpp v150, v144, v144 row_half_mirror row_mask:0xf bank_mask:0x5 bound_ctrl:1
	v_pk_fma_f32 v[166:167], v[98:99], v[12:13], v[166:167]
	v_add_f32_dpp v151, v146, v146 row_half_mirror row_mask:0xf bank_mask:0x5 bound_ctrl:1
	v_add_f32_e32 v131, v166, v167
	v_add_f32_dpp v152, v155, v154 quad_perm:[3,2,1,0] row_mask:0xf bank_mask:0xf bound_ctrl:1
	v_add_f32_dpp v150, v145, v145 row_half_mirror row_mask:0xf bank_mask:0xa bound_ctrl:1
	v_add_f32_dpp v147, v131, v131 row_mirror row_mask:0xf bank_mask:0xc bound_ctrl:1
	s_nop 1
	v_add_f32_dpp v151, v147, v147 row_half_mirror row_mask:0xf bank_mask:0xa bound_ctrl:1
	v_cndmask_b32_e64 v154, v151, v150, s[48:49]
	v_cndmask_b32_e64 v155, v150, v151, s[48:49]
	s_nop 1
	v_add_f32_dpp v153, v155, v154 quad_perm:[3,2,1,0] row_mask:0xf bank_mask:0xf bound_ctrl:1
	v_cndmask_b32_e64 v154, v153, v152, s[50:51]
	v_cndmask_b32_e64 v155, v152, v153, s[50:51]
	s_nop 1
	v_add_f32_dpp v156, v155, v154 quad_perm:[1,0,3,2] row_mask:0xf bank_mask:0xf bound_ctrl:1
	ds_write_b32 v175, v156
	v_add_u32_e32 v175, 0x800, v175
	s_cmp_eq_u32 s8, 0
	s_cbranch_scc0 .Lgdn_step_loop
	s_waitcnt lgkmcnt(0)
; #define LAS __attribute__((address_space(3)))
; __device__ __forceinline__ float sigmoidf_(float x) { return 1.0f / (1.0f + __expf(-x)); }
; __device__ __forceinline__ float softplusf_(float x) { return x > 20.f ? x : log1pf(expf(x)); }
; __device__ __forceinline__ float red8(float x) { x = red4(x); x += dppf<0x141>(x); return x; }
; __device__ __forceinline__ void u4f(const u32x4& u, float (&f)[8]) { h2f(u.x, f[0], f[1]); h2f(u.y, f[2], f[3]); h2f(u.z, f[4], f[5]); h2f(u.w, f[6], f[7]); }
; __device__ __forceinline__ void u2f(const u32x2& u, float (&f)[4]) { h2f(u.x, f[0], f[1]); h2f(u.y, f[2], f[3]); }
; template <int MIX, bool SAMPLE>
; __device__ __forceinline__ void rec_process(const Raw<MIX>& R, const MixPar& par, int l, LAS float* L, int chunk, int sg, int head) {
;     ...
;     } else if constexpr (MIX == 1) {
;         float q[8], k[8], v[4]; u4f(R.q, q); u4f(R.k, k); u2f(R.v, v);
;         float sq = 0.f, sk = 0.f;
; #pragma unroll
;         for (int i = 0; i < 8; ++i) { sq += q[i] * q[i]; sk += k[i] * k[i]; }
;         sq = red8(sq); sk = red8(sk);
;         const float rq = rsqrtf(sq + EPS) * 0.125f, rk = rsqrtf(sk + EPS);
;         float kq = 0.f;
; #pragma unroll
;         for (int i = 0; i < 8; ++i) { q[i] *= rq; k[i] *= rk; kq += q[i] * k[i]; }
;         kq = red8(kq);
;         *(LAS f32x4*)(L + C::OFF_Q + s * 64 + cgi * 8) = (f32x4){q[0], q[1], q[2], q[3]}; *(LAS f32x4*)(L + C::OFF_Q + s * 64 + cgi * 8 + 4) = (f32x4){q[4], q[5], q[6], q[7]};
;         *(LAS f32x4*)(L + C::OFF_K + s * 64 + cgi * 8) = (f32x4){k[0], k[1], k[2], k[3]}; *(LAS f32x4*)(L + C::OFF_K + s * 64 + cgi * 8 + 4) = (f32x4){k[4], k[5], k[6], k[7]};
;         *(LAS f32x4*)(L + C::OFF_V + s * 32 + cgi * 4) = (f32x4){v[0], v[1], v[2], v[3]};
;         if (cgi == 0) { const float a = expf(-par.f[0] * softplusf_(R.ga + par.f[1]));
;             *(LAS f32x4*)(L + C::OFF_SC + s * 4) = (f32x4){a, sigmoidf_(R.gb), kq, 0.f}; }
;     ...
;             if (c + 1 < SEQ / 64) { rec_process<MIX, false>(R, par, l, L + ((c + 1) & 1) * BUF, c + 1, sg, head);
;                 if (c + 2 < SEQ / 64) rec_load<MIX, false>(R, proj, c + 2, sg, head, vcol0);
;                 else if (DO_SAMPLE) rec_load<MIX, true>(R, proj, 0, sg, head, vcol0); }
.LBB0_413:
	s_or_b64 exec, exec, s[6:7]
	s_add_i32 s2, s12, 1
	s_cmp_lg_u32 s12, 31
	s_cbranch_scc0 .LBB0_420
	s_waitcnt vmcnt(2)
	v_cvt_f32_f16_e32 v23, v23
	v_cvt_f32_f16_e32 v24, v24
	v_cvt_f32_f16_sdwa v31, v0 dst_sel:DWORD dst_unused:UNUSED_PAD src0_sel:WORD_1
	v_cvt_f32_f16_e32 v30, v0
	s_waitcnt vmcnt(1)
	v_cvt_f32_f16_sdwa v47, v4 dst_sel:DWORD dst_unused:UNUSED_PAD src0_sel:WORD_1
	v_cvt_f32_f16_e32 v46, v4
	v_cvt_f32_f16_sdwa v41, v1 dst_sel:DWORD dst_unused:UNUSED_PAD src0_sel:WORD_1
	v_cvt_f32_f16_e32 v40, v1
	v_cvt_f32_f16_sdwa v49, v5 dst_sel:DWORD dst_unused:UNUSED_PAD src0_sel:WORD_1
	v_cvt_f32_f16_e32 v48, v5
	v_cvt_f32_f16_sdwa v15, v2 dst_sel:DWORD dst_unused:UNUSED_PAD src0_sel:WORD_1
	v_cvt_f32_f16_e32 v14, v2
	v_cvt_f32_f16_sdwa v43, v6 dst_sel:DWORD dst_unused:UNUSED_PAD src0_sel:WORD_1
	v_cvt_f32_f16_e32 v42, v6
	v_pk_mul_f32 v[38:39], v[30:31], v[30:31]
	v_pk_mul_f32 v[54:55], v[46:47], v[46:47]
	v_cvt_f32_f16_sdwa v37, v3 dst_sel:DWORD dst_unused:UNUSED_PAD src0_sel:WORD_1
	v_cvt_f32_f16_e32 v36, v3
	v_cvt_f32_f16_sdwa v45, v7 dst_sel:DWORD dst_unused:UNUSED_PAD src0_sel:WORD_1
	v_cvt_f32_f16_e32 v44, v7
	v_pk_mul_f32 v[50:51], v[40:41], v[40:41]
	v_pk_mul_f32 v[56:57], v[48:49], v[48:49]
	v_mov_b32_e32 v58, v54
	v_mov_b32_e32 v59, v38
	v_mov_b32_e32 v38, v55
	v_pk_add_f32 v[38:39], v[58:59], v[38:39]
	v_mov_b32_e32 v54, v56
	v_mov_b32_e32 v55, v50
	v_pk_mul_f32 v[28:29], v[14:15], v[14:15]
	v_pk_mul_f32 v[32:33], v[42:43], v[42:43]
	v_pk_add_f32 v[38:39], v[54:55], v[38:39]
	v_mov_b32_e32 v50, v57
	v_pk_add_f32 v[38:39], v[50:51], v[38:39]
	v_mov_b32_e32 v50, v32
	v_mov_b32_e32 v51, v28
	v_pk_mul_f32 v[34:35], v[36:37], v[36:37]
	v_pk_mul_f32 v[52:53], v[44:45], v[44:45]
	v_pk_add_f32 v[38:39], v[50:51], v[38:39]
	v_mov_b32_e32 v28, v33
	v_pk_add_f32 v[28:29], v[28:29], v[38:39]
	v_mov_b32_e32 v32, v52
	v_mov_b32_e32 v33, v34
	v_pk_add_f32 v[28:29], v[32:33], v[28:29]
	v_mov_b32_e32 v34, v53
	v_pk_add_f32 v[28:29], v[34:35], v[28:29]
	s_bitcmp1_b32 s2, 0
	s_cselect_b32 s3, 0xe400, 0
	v_mov_b32_dpp v33, v29 quad_perm:[1,0,3,2] row_mask:0xf bank_mask:0xf bound_ctrl:1
	v_mov_b32_dpp v32, v28 quad_perm:[1,0,3,2] row_mask:0xf bank_mask:0xf bound_ctrl:1
	v_pk_add_f32 v[28:29], v[28:29], v[32:33]
	s_add_i32 s3, s3, 0
	s_nop 0
	v_mov_b32_dpp v33, v29 quad_perm:[2,3,0,1] row_mask:0xf bank_mask:0xf bound_ctrl:1
	v_mov_b32_dpp v32, v28 quad_perm:[2,3,0,1] row_mask:0xf bank_mask:0xf bound_ctrl:1
	v_pk_add_f32 v[28:29], v[28:29], v[32:33]
	s_nop 1
	v_mov_b32_dpp v33, v29 row_half_mirror row_mask:0xf bank_mask:0xf bound_ctrl:1
	v_mov_b32_dpp v32, v28 row_half_mirror row_mask:0xf bank_mask:0xf bound_ctrl:1
	v_pk_add_f32 v[28:29], v[28:29], v[32:33]
	s_nop 0
	v_pk_add_f32 v[32:33], v[28:29], s[66:67] op_sel_hi:[1,0]
	v_mov_b32_e32 v29, v202
	v_mul_f32_e32 v16, 0x4b800000, v33
	v_cmp_gt_f32_e32 vcc, s16, v33
	s_nop 0
	v_ashrrev_i32_e32 v28, 3, v29
	v_cndmask_b32_e32 v16, v33, v16, vcc
	v_rsq_f32_e32 v16, v16
	s_nop 0
	v_mul_f32_e32 v33, 0x45800000, v16
	v_cndmask_b32_e32 v16, v16, v33, vcc
	v_mul_f32_e32 v33, 0x4b800000, v32
	v_cmp_gt_f32_e32 vcc, s16, v32
	v_mul_f32_e32 v16, 0x3e000000, v16
	v_pk_mul_f32 v[34:35], v[16:17], v[14:15] op_sel_hi:[0,1]
	v_cndmask_b32_e32 v32, v32, v33, vcc
	v_rsq_f32_e32 v38, v32
	v_pk_mul_f32 v[30:31], v[16:17], v[30:31] op_sel_hi:[0,1]
	v_pk_mul_f32 v[32:33], v[16:17], v[40:41] op_sel_hi:[0,1]
	v_pk_mul_f32 v[36:37], v[16:17], v[36:37] op_sel_hi:[0,1]
	v_mul_f32_e32 v14, 0x45800000, v38
	v_cndmask_b32_e32 v14, v38, v14, vcc
	v_pk_mul_f32 v[38:39], v[14:15], v[46:47] op_sel_hi:[0,1]
	v_pk_mul_f32 v[40:41], v[30:31], v[38:39]
	s_nop 0
	v_add_f32_e32 v15, 0, v40
	v_add_f32_e32 v15, v41, v15
	v_pk_mul_f32 v[40:41], v[14:15], v[48:49] op_sel_hi:[0,1]
	v_pk_mul_f32 v[46:47], v[32:33], v[40:41]
	v_cvt_f32_f16_sdwa v49, v9 dst_sel:DWORD dst_unused:UNUSED_PAD src0_sel:WORD_1
	v_add_f32_e32 v15, v46, v15
	v_add_f32_e32 v15, v47, v15
	v_pk_mul_f32 v[42:43], v[14:15], v[42:43] op_sel_hi:[0,1]
	v_pk_mul_f32 v[46:47], v[34:35], v[42:43]
	v_cvt_f32_f16_e32 v48, v9
	v_add_f32_e32 v15, v46, v15
	v_pk_mul_f32 v[44:45], v[14:15], v[44:45] op_sel_hi:[0,1]
	v_add_f32_e32 v16, v47, v15
	v_pk_mul_f32 v[14:15], v[36:37], v[44:45]
	v_cvt_f32_f16_sdwa v47, v8 dst_sel:DWORD dst_unused:UNUSED_PAD src0_sel:WORD_1
	v_add_f32_e32 v14, v14, v16
	v_and_b32_e32 v16, 7, v29
	v_add_f32_e32 v14, v15, v14
	v_cvt_f32_f16_e32 v46, v8
	v_lshlrev_b32_e32 v29, 8, v28
	v_lshlrev_b32_e32 v50, 5, v16
	v_add_f32_dpp v14, v14, v14 quad_perm:[1,0,3,2] row_mask:0xf bank_mask:0xf bound_ctrl:1
	v_add3_u32 v29, s3, v29, v50
	ds_write_b128 v29, v[30:33]
	ds_write_b128 v29, v[34:37] offset:16
	ds_write_b128 v29, v[38:41] offset:16384
	ds_write_b128 v29, v[42:45] offset:16400
	v_add_f32_dpp v14, v14, v14 quad_perm:[2,3,0,1] row_mask:0xf bank_mask:0xf bound_ctrl:1
	v_lshlrev_b32_e32 v29, 7, v28
	v_lshlrev_b32_e32 v30, 4, v16
	v_mov_b32_dpp v15, v14 row_half_mirror row_mask:0xf bank_mask:0xf bound_ctrl:1
	v_add3_u32 v29, s3, v29, v30
	v_cmp_eq_u32_e32 vcc, 0, v16
	v_mul_f32_e32 v60, 0xbfb8aa3b, v24
	v_exp_f32_e32 v60, v60
	s_nop 0
	v_add_f32_e32 v60, 1.0, v60
	v_rcp_f32_e32 v60, v60
	s_nop 0
	v_pk_mul_f32 v[46:47], v[46:47], v[60:61] op_sel_hi:[1,0]
	v_pk_mul_f32 v[48:49], v[48:49], v[60:61] op_sel_hi:[1,0]
	ds_write_b128 v29, v[46:49] offset:32768
	s_and_saveexec_b64 s[6:7], vcc
	s_cbranch_execz .LBB0_418
	v_add_f32_e32 v16, v18, v23
	v_cmp_nlt_f32_e32 vcc, s23, v16
	s_and_saveexec_b64 s[8:9], vcc
	s_cbranch_execz .LBB0_417
	v_mul_f32_e32 v29, 0x3fb8aa3b, v16
	v_rndne_f32_e32 v30, v29
	v_sub_f32_e32 v31, v29, v30
	v_fma_f32 v29, v16, s19, -v29
	v_fmac_f32_e32 v29, 0x32a5705f, v16
	v_add_f32_e32 v29, v31, v29
	v_cvt_i32_f32_e32 v30, v30
	v_exp_f32_e32 v29, v29
	v_cmp_ngt_f32_e32 vcc, s96, v16
	v_ldexp_f32 v29, v29, v30
	s_nop 0
	v_cndmask_b32_e32 v29, 0, v29, vcc
	v_cmp_nlt_f32_e32 vcc, s97, v16
	s_nop 1
	v_cndmask_b32_e32 v16, v216, v29, vcc
	v_add_f32_e32 v29, 1.0, v16
	v_add_f32_e32 v30, -1.0, v29
	v_log_f32_e32 v31, v29
	v_rcp_f32_e32 v29, v30
	v_cmp_eq_f32_e32 vcc, 0, v30
	v_mul_f32_e32 v31, 0x3f317218, v31
	v_mul_f32_e32 v29, v16, v29
	v_mul_f32_e32 v31, v31, v29
	v_cndmask_b32_e32 v16, v31, v16, vcc
.LBB0_417:
	s_or_b64 exec, exec, s[8:9]
	v_mul_f32_e32 v29, v19, v16
	v_mul_f32_e32 v16, 0x3fb8aa3b, v29
	v_fma_f32 v30, v29, s19, -v16
	v_rndne_f32_e32 v31, v16
	v_fmac_f32_e32 v30, 0x32a5705f, v29
	v_sub_f32_e32 v16, v16, v31
	v_add_f32_e32 v16, v16, v30
	v_exp_f32_e32 v30, v16
	v_mul_f32_e32 v16, 0xbfb8aa3b, v24
	v_exp_f32_e32 v32, v16
	v_cvt_i32_f32_e32 v31, v31
	v_add_f32_e32 v16, v14, v15
	v_cmp_ngt_f32_e32 vcc, s96, v29
	v_add_f32_e32 v15, 1.0, v32
	v_ldexp_f32 v14, v30, v31
	v_cndmask_b32_e32 v14, 0, v14, vcc
	v_cmp_nlt_f32_e32 vcc, s97, v29
	v_lshl_add_u32 v28, v28, 4, s3
	s_nop 0
	v_cndmask_b32_e32 v14, v216, v14, vcc
	v_rcp_f32_e32 v29, v15
	s_nop 0
	v_mul_f32_e32 v15, v14, v29
	ds_write_b128 v28, v[14:17] offset:49152
